# phase-start LayerNorm stats table: skip the 12 unused partial-stat loads and reduces when the WG owns a single unit (w_out, ff2)
# speedup vs baseline: 1.1292x; 1.0071x over previous
.LBB0_1039:
	s_or_b64 exec, exec, s[10:11]
	s_waitcnt vmcnt(0)
	v_pk_add_f32 v[12:13], v[12:13], v[14:15]
	v_pk_add_f32 v[8:9], v[8:9], v[10:11]
	v_pk_add_f32 v[12:13], v[12:13], 0 op_sel_hi:[1,0]
	v_pk_add_f32 v[4:5], v[4:5], v[6:7]
	v_pk_add_f32 v[8:9], v[12:13], v[8:9]
	v_pk_add_f32 v[0:1], v[0:1], v[2:3]
	v_pk_add_f32 v[4:5], v[8:9], v[4:5]
	s_nop 0
	v_pk_add_f32 v[0:1], v[4:5], v[0:1]
	ds_bpermute_b32 v2, v64, v0
	ds_bpermute_b32 v3, v64, v1
	s_and_saveexec_b64 s[10:11], vcc
	s_cbranch_execz .LBB0_1041
	s_waitcnt lgkmcnt(0)
	v_pk_add_f32 v[0:1], v[0:1], v[2:3]
	s_nop 0
	v_pk_mul_f32 v[0:1], v[0:1], s[6:7] op_sel_hi:[1,0]
	s_nop 0
	v_fma_f32 v1, -v0, v0, v1
	v_max_f32_e32 v1, 0, v1
	v_add_f32_e32 v1, 0x3727c5ac, v1
	v_mul_f32_e32 v2, 0x4b800000, v1
	v_cmp_gt_f32_e32 vcc, s14, v1
	s_nop 1
	v_cndmask_b32_e32 v1, v1, v2, vcc
	v_rsq_f32_e32 v1, v1
	s_nop 0
	v_mul_f32_e32 v2, 0x45800000, v1
	v_cndmask_b32_e32 v1, v1, v2, vcc
	ds_write_b64 v52, v[0:1] offset:6144
	s_branch .LBB0_1041
.Lst_skip_wo:
	s_waitcnt vmcnt(0)
	v_pk_add_f32 v[60:61], v[60:61], v[62:63]
	v_xor_b32_e32 v64, 1, v237
	v_add_u32_e32 v67, 64, v67
	v_pk_add_f32 v[60:61], v[60:61], 0 op_sel_hi:[1,0]
	v_pk_add_f32 v[56:57], v[56:57], v[58:59]
	v_cmp_lt_i32_e32 vcc, v64, v67
	v_pk_add_f32 v[56:57], v[60:61], v[56:57]
	v_pk_add_f32 v[52:53], v[52:53], v[54:55]
	v_cndmask_b32_e32 v64, v237, v64, vcc
	v_pk_add_f32 v[52:53], v[56:57], v[52:53]
	v_pk_add_f32 v[48:49], v[48:49], v[50:51]
	v_lshlrev_b32_e32 v64, 2, v64
	v_pk_add_f32 v[48:49], v[52:53], v[48:49]
	ds_bpermute_b32 v50, v64, v48
	ds_bpermute_b32 v51, v64, v49
	v_cmp_eq_u32_e32 vcc, 0, v66
	v_lshl_add_u32 v52, v65, 3, s90
	s_and_saveexec_b64 s[10:11], vcc
	s_cbranch_execz .Lst_g1e_wo
	s_waitcnt lgkmcnt(0)
	v_pk_add_f32 v[48:49], v[48:49], v[50:51]
	s_nop 0
	v_pk_mul_f32 v[48:49], v[48:49], s[6:7] op_sel_hi:[1,0]
	s_nop 0
	v_fma_f32 v49, -v48, v48, v49
	v_max_f32_e32 v49, 0, v49
	v_add_f32_e32 v49, 0x3727c5ac, v49
	v_mul_f32_e32 v50, 0x4b800000, v49
	v_cmp_gt_f32_e64 s[24:25], s14, v49
	s_nop 1
	v_cndmask_b32_e64 v49, v49, v50, s[24:25]
	v_rsq_f32_e32 v49, v49
	s_nop 0
	v_mul_f32_e32 v50, 0x45800000, v49
	v_cndmask_b32_e64 v49, v49, v50, s[24:25]
	ds_write_b64 v52, v[48:49]
.Lst_g1e_wo:
	s_or_b64 exec, exec, s[10:11]
	s_branch .LBB0_1041

.LBB0_1337:
	s_or_b64 exec, exec, s[10:11]
	s_waitcnt vmcnt(0)
	v_pk_add_f32 v[12:13], v[12:13], v[14:15]
	v_pk_add_f32 v[8:9], v[8:9], v[10:11]
	v_pk_add_f32 v[12:13], v[12:13], 0 op_sel_hi:[1,0]
	v_pk_add_f32 v[4:5], v[4:5], v[6:7]
	v_pk_add_f32 v[8:9], v[12:13], v[8:9]
	v_pk_add_f32 v[0:1], v[0:1], v[2:3]
	v_pk_add_f32 v[4:5], v[8:9], v[4:5]
	s_nop 0
	v_pk_add_f32 v[0:1], v[4:5], v[0:1]
	ds_bpermute_b32 v2, v200, v0
	ds_bpermute_b32 v3, v200, v1
	s_and_saveexec_b64 s[10:11], vcc
	s_cbranch_execz .LBB0_1339
	s_waitcnt lgkmcnt(0)
	v_pk_add_f32 v[0:1], v[0:1], v[2:3]
	s_nop 0
	v_pk_mul_f32 v[0:1], v[0:1], s[6:7] op_sel_hi:[1,0]
	s_nop 0
	v_fma_f32 v1, -v0, v0, v1
	v_max_f32_e32 v1, 0, v1
	v_add_f32_e32 v1, 0x3727c5ac, v1
	v_mul_f32_e32 v2, 0x4b800000, v1
	v_cmp_gt_f32_e32 vcc, s14, v1
	s_nop 1
	v_cndmask_b32_e32 v1, v1, v2, vcc
	v_rsq_f32_e32 v1, v1
	s_nop 0
	v_mul_f32_e32 v2, 0x45800000, v1
	v_cndmask_b32_e32 v1, v1, v2, vcc
	ds_write_b64 v52, v[0:1] offset:6144
	s_branch .LBB0_1339
.Lst_skip_f2:
	s_waitcnt vmcnt(0)
	v_pk_add_f32 v[60:61], v[60:61], v[62:63]
	v_pk_add_f32 v[56:57], v[56:57], v[58:59]
	v_pk_add_f32 v[60:61], v[60:61], 0 op_sel_hi:[1,0]
	v_pk_add_f32 v[52:53], v[52:53], v[54:55]
	v_pk_add_f32 v[56:57], v[60:61], v[56:57]
	v_pk_add_f32 v[48:49], v[48:49], v[50:51]
	v_pk_add_f32 v[52:53], v[56:57], v[52:53]
	v_cmp_eq_u32_e32 vcc, 0, v65
	v_pk_add_f32 v[48:49], v[52:53], v[48:49]
	ds_bpermute_b32 v50, v200, v48
	ds_bpermute_b32 v51, v200, v49
	v_lshl_add_u32 v52, v64, 3, s90
	s_and_saveexec_b64 s[10:11], vcc
	s_cbranch_execz .Lst_g1e_f2
	s_waitcnt lgkmcnt(0)
	v_pk_add_f32 v[48:49], v[48:49], v[50:51]
	s_nop 0
	v_pk_mul_f32 v[48:49], v[48:49], s[6:7] op_sel_hi:[1,0]
	s_nop 0
	v_fma_f32 v49, -v48, v48, v49
	v_max_f32_e32 v49, 0, v49
	v_add_f32_e32 v49, 0x3727c5ac, v49
	v_mul_f32_e32 v50, 0x4b800000, v49
	v_cmp_gt_f32_e64 s[22:23], s14, v49
	s_nop 1
	v_cndmask_b32_e64 v49, v49, v50, s[22:23]
	v_rsq_f32_e32 v49, v49
	s_nop 0
	v_mul_f32_e32 v50, 0x45800000, v49
	v_cndmask_b32_e64 v49, v49, v50, s[22:23]
	ds_write_b64 v52, v[48:49]
